# v9 + GEMM phases: s_setprio flips deleted, one static s_setprio 1 for waves 0-3 (older half) per GEMM phase
# speedup vs baseline: 1.0090x; 1.0006x over previous
; #define LAS __attribute__((address_space(3)))
;     __device__ void init(int b_, int G_, int c_) { so.init(TB, 42 * 256, G_, c_); G = G_; c = c_; b = b_; gstart = b_ == 0 ? 0 : 256 + 192 * b_; ng = b_ == 0 ? 448 : 192; }
; __device__ __forceinline__ KParams kparams() { unsigned long long a = (unsigned long long)__builtin_amdgcn_kernarg_segment_ptr(); asm volatile("" : "+s"(a)); return (KParams)a; }
; template <class Epi, class Sched>
; __device__ __forceinline__ void gemm_phase(const int wv, LAS unsigned char* lds, const Gemm g, const Sched& S, const Epi& E) {
;     int tid_ = TIDX; asm volatile("" : "+v"(tid_));
;     const int tid = tid_, wid = __builtin_amdgcn_readfirstlane(tid >> 6), lane = tid & 63, wr = wid >> 2, wc = wid & 3, fr = lane & 15, fq = lane >> 4;
;     const int K = g.K, nt = K / BK;
; __global__ void __launch_bounds__(512, 2) mega(Params p_unused) {
;     ...
;     for (int b = 0; b < 4; ++b) {
;         {
;             KParams kp = kparams(); unsigned char* ws = kp->ws;
;             pg8::Gemm gm{WSP(bf16_t, WS_OR) + (size_t)b * TB * 2048, WSP(bf16_t, WS_WIN), TB, INW, DM, DM, DM};
;             InProjOrder S; S.init(b, (int)gridDim.x, (int)blockIdx.x);
;             EpiIn E{WSP(bf16_t, WS_R0), WSP(bf16_t, WS_GR), (bf16_t*)kp->out + (size_t)b * TB * 2048};
;             pg8::gemm_phase<EpiIn, InProjOrder>(wv, lds, gm, S, E);
.LBB0_132:
	s_cmpk_ge_u32 s53, 0x100
	s_cbranch_scc1 .Lgprio_ip
	s_setprio 1

;     __device__ void init(int b_, int G_, int c_) { so.init(TB, 42 * 256, G_, c_); G = G_; c = c_; b = b_; gstart = b_ == 0 ? 0 : 256 + 192 * b_; ng = b_ == 0 ? 448 : 192; }
; __device__ __forceinline__ KParams kparams() { unsigned long long a = (unsigned long long)__builtin_amdgcn_kernarg_segment_ptr(); asm volatile("" : "+s"(a)); return (KParams)a; }
; template <class Epi, class Sched>
; __device__ __forceinline__ void gemm_phase(const int wv, LAS unsigned char* lds, const Gemm g, const Sched& S, const Epi& E) {
;     int tid_ = TIDX; asm volatile("" : "+v"(tid_));
;     const int tid = tid_, wid = __builtin_amdgcn_readfirstlane(tid >> 6), lane = tid & 63, wr = wid >> 2, wc = wid & 3, fr = lane & 15, fq = lane >> 4;
;     const int K = g.K, nt = K / BK;
; __global__ void __launch_bounds__(512, 2) mega(Params p_unused) {
;     ...
;         KParams kp = kparams(); unsigned char* ws = kp->ws;
;         pg8::StaticOrder S; S.init(MT, DM, (int)gridDim.x, (int)blockIdx.x);
;         pg8::Gemm gm{WSP(bf16_t, WS_Y), WSP(bf16_t, WS_WOUT), MT, DM, DM, DM, DM}; EpiOut E{kp->x, WSP(bf16_t, WS_X1B), WSP(float, WS_SS2)};
;         pg8::gemm_phase<EpiOut, pg8::StaticOrder>(wv, lds, gm, S, E);
.LBB0_646:
	s_or_b64 exec, exec, s[0:1]
	s_mov_b64 s[2:3], s[56:57]
	s_waitcnt lgkmcnt(0)
	s_barrier
	s_cmpk_ge_u32 s53, 0x100
	s_cbranch_scc1 .Lgprio_out
	s_setprio 1

;     __device__ void init(int b_, int G_, int c_) { so.init(TB, 42 * 256, G_, c_); G = G_; c = c_; b = b_; gstart = b_ == 0 ? 0 : 256 + 192 * b_; ng = b_ == 0 ? 448 : 192; }
; __device__ __forceinline__ KParams kparams() { unsigned long long a = (unsigned long long)__builtin_amdgcn_kernarg_segment_ptr(); asm volatile("" : "+s"(a)); return (KParams)a; }
; template <class Epi, class Sched>
; __device__ __forceinline__ void gemm_phase(const int wv, LAS unsigned char* lds, const Gemm g, const Sched& S, const Epi& E) {
;     int tid_ = TIDX; asm volatile("" : "+v"(tid_));
;     const int tid = tid_, wid = __builtin_amdgcn_readfirstlane(tid >> 6), lane = tid & 63, wr = wid >> 2, wc = wid & 3, fr = lane & 15, fq = lane >> 4;
;     const int K = g.K, nt = K / BK;
; __global__ void __launch_bounds__(512, 2) mega(Params p_unused) {
;     ...
;         KParams kp = kparams(); unsigned char* ws = kp->ws;
;         pg8::StaticOrder S; S.init(MT, DFF, (int)gridDim.x, (int)blockIdx.x);
;         pg8::Gemm gm{WSP(bf16_t, WS_X1B), WSP(bf16_t, WS_WUP), MT, DFF, DM, DM, DM}; EpiUp E{WSP(float, WS_SS2), WSP(bf16_t, WS_H)};
;         pg8::gemm_phase<EpiUp, pg8::StaticOrder>(wv, lds, gm, S, E);
.LBB0_710:
	s_or_b64 exec, exec, s[0:1]
	s_mov_b64 s[0:1], s[56:57]
	s_waitcnt lgkmcnt(0)
	s_barrier
	s_cmpk_ge_u32 s53, 0x100
	s_cbranch_scc1 .Lgprio_up
	s_setprio 1

;     __device__ void init(int b_, int G_, int c_) { so.init(TB, 42 * 256, G_, c_); G = G_; c = c_; b = b_; gstart = b_ == 0 ? 0 : 256 + 192 * b_; ng = b_ == 0 ? 448 : 192; }
; __device__ __forceinline__ KParams kparams() { unsigned long long a = (unsigned long long)__builtin_amdgcn_kernarg_segment_ptr(); asm volatile("" : "+s"(a)); return (KParams)a; }
; template <class Epi, class Sched>
; __device__ __forceinline__ void gemm_phase(const int wv, LAS unsigned char* lds, const Gemm g, const Sched& S, const Epi& E) {
;     int tid_ = TIDX; asm volatile("" : "+v"(tid_));
;     const int tid = tid_, wid = __builtin_amdgcn_readfirstlane(tid >> 6), lane = tid & 63, wr = wid >> 2, wc = wid & 3, fr = lane & 15, fq = lane >> 4;
;     const int K = g.K, nt = K / BK;
; __global__ void __launch_bounds__(512, 2) mega(Params p_unused) {
;     ...
;         KParams kp = kparams(); unsigned char* ws = kp->ws;
;         pg8::StaticOrder S; S.init(MT, DM, (int)gridDim.x, (int)blockIdx.x);
;         pg8::Gemm gm{WSP(bf16_t, WS_H), WSP(bf16_t, WS_WDN), MT, DM, DFF, DFF, DFF, 1}; EpiDown E{WSP(bf16_t, WS_X1B), kp->out};
;         pg8::gemm_phase<EpiDown, pg8::StaticOrder>(wv, lds, gm, S, E);
.LBB0_774:
	s_or_b64 exec, exec, s[0:1]
	s_waitcnt lgkmcnt(0)
	s_barrier
	s_cmpk_ge_u32 s53, 0x100
	s_cbranch_scc1 .Lgprio_dn
	s_setprio 1
